# GEMM tiles: the leading wave half's realignment barrier behind the K loop is taken a little later, inside the epilogue, so its first epilogue work runs under the trailing half's last MFMA block
# speedup vs baseline: 1.0022x; 1.0022x over previous
; #define PG8_STAGE(bufoff, gbase, voff) do { _Pragma("unroll") for (int _i = 0; _i < 2; ++_i) \
;         __builtin_amdgcn_global_load_lds((const unsigned*)((const char*)(gbase) + (voff)[_i]), (PG8_LAS unsigned*)(lds + (bufoff) + ldsw + _i * 8192), 16, 0, 0); } while (0)
; #define PG8_LDA(dst, b, h) do { _Pragma("unroll") for (int m = 0; m < 4; ++m) _Pragma("unroll") for (int k = 0; k < 2; ++k) dst[m][k] = *(const PG8_LAS bf16x8*)(lds + PG8_SA(b, h) + aoff + m * 2048 + k * 1024); } while (0)
; #define PG8_LDB(dst, b, h) do { _Pragma("unroll") for (int n = 0; n < 2; ++n) _Pragma("unroll") for (int k = 0; k < 2; ++k) dst[n][k] = *(const PG8_LAS bf16x8*)(lds + PG8_SB(b, h) + boff + n * 2048 + k * 1024); } while (0)
; #define PG8_MMA(ai, bj, At, Bt) do { __builtin_amdgcn_s_setprio(1); _Pragma("unroll") for (int m = 0; m < 4; ++m) _Pragma("unroll") for (int n = 0; n < 2; ++n) _Pragma("unroll") for (int k = 0; k < 2; ++k) \
;         acc[ai][bj][m][n] = __builtin_amdgcn_mfma_f32_16x16x32_bf16(Bt[n][k], At[m][k], acc[ai][bj][m][n], 0, 0, 0); __builtin_amdgcn_s_setprio(0); } while (0)
; #define PG8_WAIT_V(n) asm volatile("s_waitcnt vmcnt(" #n ")" ::: "memory")
; #define PG8_WAIT_L(n) asm volatile("s_waitcnt lgkmcnt(" #n ")" ::: "memory")
; #define PG8_BAR __builtin_amdgcn_s_barrier()
; #define PG8_SCHED __builtin_amdgcn_sched_barrier(0)
; template <class Epi, class Sched, bool ALIGN_EPI = false, bool SP2 = false>
; __device__ __forceinline__ void gemm_phase(PG8_LAS unsigned char* lds, const Gemm g, const Sched& S, const Epi& E) {
;     ...
;             PG8_LDB(B0, 0, 0); PG8_LDB(B1, 0, 1); PG8_SCHED; PG8_LDA(At, 0, 0); PG8_STAGE(PG8_SA(1, 1), a1 + hstep, voffA);
;             PG8_WAIT_V(8); PG8_WAIT_L(0); PG8_BAR; PG8_MMA(0, 0, At, B0); PG8_MMA(0, 1, At, B1); PG8_BAR; PG8_SCHED;
;             PG8_LDA(At, 0, 1); PG8_STAGE(PG8_SB(0, 0), b2, voffB); PG8_STAGE(PG8_SB(0, 1), b2 + hstep, voffB); PG8_STAGE(PG8_SA(0, 0), a2, voffA);
;             PG8_WAIT_V(8); PG8_WAIT_L(0); PG8_BAR; PG8_MMA(1, 0, At, B0); PG8_MMA(1, 1, At, B1); PG8_BAR; PG8_SCHED;
.LBB0_38:
	s_add_u32 s10, vcc_lo, 0xfff80080
	s_addc_u32 s11, vcc_hi, -1
	s_add_i32 s84, 0, 0x10000
	s_cmp_eq_u32 s13, 28
	s_cselect_b32 s69, s27, s11
	s_cselect_b32 s68, s86, s10
	s_cselect_b32 s11, s17, s12
	s_cselect_b32 s10, s88, s21
	s_add_i32 s93, 0, 0x14000
	ds_read_b128 v[114:117], v218
	ds_read_b128 v[118:121], v218 offset:1024
	ds_read_b128 v[130:133], v218 offset:2048
	ds_read_b128 v[138:141], v218 offset:3072
	ds_read_b128 v[146:149], v218 offset:16384
	ds_read_b128 v[156:159], v218 offset:17408
	ds_read_b128 v[160:163], v218 offset:18432
	ds_read_b128 v[164:167], v218 offset:19456
	s_add_i32 m0, s2, 0xc000
	ds_read_b128 v[168:171], v199
	ds_read_b128 v[172:175], v199 offset:1024
	ds_read_b128 v[176:179], v199 offset:2048
	ds_read_b128 v[180:183], v199 offset:3072
	ds_read_b128 v[184:187], v199 offset:4096
	ds_read_b128 v[188:191], v199 offset:5120
	ds_read_b128 v[200:203], v199 offset:6144
	ds_read_b128 v[204:207], v199 offset:7168
	global_load_lds_dwordx4 v152, vcc
	s_add_i32 m0, s2, 0xe000
	s_nop 0
	global_load_lds_dwordx4 v154, vcc
	s_waitcnt vmcnt(8) lgkmcnt(0)
	s_setprio 1
	s_barrier
	v_mfma_f32_16x16x32_bf16 v[142:145], v[114:117], v[168:171], v[142:145]
	v_mfma_f32_16x16x32_bf16 v[62:65], v[130:133], v[168:171], v[62:65]
	v_mfma_f32_16x16x32_bf16 v[122:125], v[114:117], v[176:179], v[122:125]
	v_mfma_f32_16x16x32_bf16 v[50:53], v[130:133], v[176:179], v[50:53]
	v_mfma_f32_16x16x32_bf16 v[106:109], v[114:117], v[184:187], v[106:109]
	v_mfma_f32_16x16x32_bf16 v[42:45], v[130:133], v[184:187], v[42:45]
	v_mfma_f32_16x16x32_bf16 v[98:101], v[114:117], v[200:203], v[98:101]
	v_mfma_f32_16x16x32_bf16 v[34:37], v[130:133], v[200:203], v[34:37]
	v_mfma_f32_16x16x32_bf16 v[142:145], v[118:121], v[172:175], v[142:145]
	v_mfma_f32_16x16x32_bf16 v[62:65], v[138:141], v[172:175], v[62:65]
	v_mfma_f32_16x16x32_bf16 v[122:125], v[118:121], v[180:183], v[122:125]
	v_mfma_f32_16x16x32_bf16 v[50:53], v[138:141], v[180:183], v[50:53]
	v_mfma_f32_16x16x32_bf16 v[106:109], v[118:121], v[188:191], v[106:109]
	v_mfma_f32_16x16x32_bf16 v[42:45], v[138:141], v[188:191], v[42:45]
	v_mfma_f32_16x16x32_bf16 v[98:101], v[118:121], v[204:207], v[98:101]
	v_mfma_f32_16x16x32_bf16 v[34:37], v[138:141], v[204:207], v[34:37]
	v_mfma_f32_16x16x32_bf16 v[134:137], v[146:149], v[168:171], v[134:137]
	v_mfma_f32_16x16x32_bf16 v[58:61], v[160:163], v[168:171], v[58:61]
	v_mfma_f32_16x16x32_bf16 v[126:129], v[146:149], v[176:179], v[126:129]
	v_mfma_f32_16x16x32_bf16 v[54:57], v[160:163], v[176:179], v[54:57]
	v_mfma_f32_16x16x32_bf16 v[110:113], v[146:149], v[184:187], v[110:113]
	v_mfma_f32_16x16x32_bf16 v[46:49], v[160:163], v[184:187], v[46:49]
	v_mfma_f32_16x16x32_bf16 v[102:105], v[146:149], v[200:203], v[102:105]
	v_mfma_f32_16x16x32_bf16 v[38:41], v[160:163], v[200:203], v[38:41]
	v_mfma_f32_16x16x32_bf16 v[134:137], v[156:159], v[172:175], v[134:137]
	v_mfma_f32_16x16x32_bf16 v[58:61], v[164:167], v[172:175], v[58:61]
	v_mfma_f32_16x16x32_bf16 v[126:129], v[156:159], v[180:183], v[126:129]
	v_mfma_f32_16x16x32_bf16 v[54:57], v[164:167], v[180:183], v[54:57]
	v_mfma_f32_16x16x32_bf16 v[110:113], v[156:159], v[188:191], v[110:113]
	v_mfma_f32_16x16x32_bf16 v[46:49], v[164:167], v[188:191], v[46:49]
	v_mfma_f32_16x16x32_bf16 v[102:105], v[156:159], v[204:207], v[102:105]
	v_mfma_f32_16x16x32_bf16 v[38:41], v[164:167], v[204:207], v[38:41]
	s_barrier
	s_setprio 0
	s_add_i32 s84, s84, s1
	s_add_u32 s100, s10, 0x80
	s_addc_u32 s101, s11, 0
	s_mov_b32 m0, s84
	ds_read_b128 v[168:171], v199 offset:16384
	ds_read_b128 v[172:175], v199 offset:17408
	ds_read_b128 v[176:179], v199 offset:18432
	ds_read_b128 v[180:183], v199 offset:19456
	ds_read_b128 v[184:187], v199 offset:20480
	ds_read_b128 v[188:191], v199 offset:21504
	ds_read_b128 v[200:203], v199 offset:22528
	ds_read_b128 v[204:207], v199 offset:23552
	global_load_lds_dwordx4 v0, s[10:11]
	s_add_i32 m0, s84, 0x2000
	s_add_u32 s84, s10, 0x80000
	s_addc_u32 s85, s11, 0
	s_add_i32 s93, s93, s1
	global_load_lds_dwordx4 v150, s[10:11]
	s_mov_b32 m0, s93
	s_add_u32 s98, s68, 0x80
	s_addc_u32 s99, s69, 0
	global_load_lds_dwordx4 v0, s[84:85]
	s_add_i32 m0, s93, 0x2000
	s_nop 0
	global_load_lds_dwordx4 v150, s[84:85]
	s_mov_b32 m0, s2
	s_nop 0
	global_load_lds_dwordx4 v0, s[68:69]
	s_mov_b32 m0, s4
	s_nop 0
	global_load_lds_dwordx4 v150, s[68:69]
	s_waitcnt vmcnt(8) lgkmcnt(0)
	s_setprio 1
	s_barrier
	v_mfma_f32_16x16x32_bf16 v[94:97], v[114:117], v[168:171], v[94:97]
	v_mfma_f32_16x16x32_bf16 v[30:33], v[130:133], v[168:171], v[30:33]
	v_mfma_f32_16x16x32_bf16 v[82:85], v[114:117], v[176:179], v[82:85]
	v_mfma_f32_16x16x32_bf16 v[18:21], v[130:133], v[176:179], v[18:21]
	v_mfma_f32_16x16x32_bf16 v[74:77], v[114:117], v[184:187], v[74:77]
	v_mfma_f32_16x16x32_bf16 v[10:13], v[130:133], v[184:187], v[10:13]
	v_mfma_f32_16x16x32_bf16 v[66:69], v[114:117], v[200:203], v[66:69]
	v_mfma_f32_16x16x32_bf16 v[2:5], v[130:133], v[200:203], v[2:5]
	v_mfma_f32_16x16x32_bf16 v[94:97], v[118:121], v[172:175], v[94:97]
	v_mfma_f32_16x16x32_bf16 v[30:33], v[138:141], v[172:175], v[30:33]
	v_mfma_f32_16x16x32_bf16 v[82:85], v[118:121], v[180:183], v[82:85]
	v_mfma_f32_16x16x32_bf16 v[18:21], v[138:141], v[180:183], v[18:21]
	v_mfma_f32_16x16x32_bf16 v[74:77], v[118:121], v[188:191], v[74:77]
	v_mfma_f32_16x16x32_bf16 v[10:13], v[138:141], v[188:191], v[10:13]
	v_mfma_f32_16x16x32_bf16 v[66:69], v[118:121], v[204:207], v[66:69]
	v_mfma_f32_16x16x32_bf16 v[2:5], v[138:141], v[204:207], v[2:5]
	v_mfma_f32_16x16x32_bf16 v[90:93], v[146:149], v[168:171], v[90:93]
	v_mfma_f32_16x16x32_bf16 v[26:29], v[160:163], v[168:171], v[26:29]
	v_mfma_f32_16x16x32_bf16 v[86:89], v[146:149], v[176:179], v[86:89]
	v_mfma_f32_16x16x32_bf16 v[22:25], v[160:163], v[176:179], v[22:25]
	v_mfma_f32_16x16x32_bf16 v[78:81], v[146:149], v[184:187], v[78:81]
	v_mfma_f32_16x16x32_bf16 v[14:17], v[160:163], v[184:187], v[14:17]
	v_mfma_f32_16x16x32_bf16 v[70:73], v[146:149], v[200:203], v[70:73]
	v_mfma_f32_16x16x32_bf16 v[6:9], v[160:163], v[200:203], v[6:9]
	v_mfma_f32_16x16x32_bf16 v[90:93], v[156:159], v[172:175], v[90:93]
	v_mfma_f32_16x16x32_bf16 v[26:29], v[164:167], v[172:175], v[26:29]
	v_mfma_f32_16x16x32_bf16 v[86:89], v[156:159], v[180:183], v[86:89]
	v_mfma_f32_16x16x32_bf16 v[22:25], v[164:167], v[180:183], v[22:25]
	v_mfma_f32_16x16x32_bf16 v[78:81], v[156:159], v[188:191], v[78:81]
	v_mfma_f32_16x16x32_bf16 v[14:17], v[164:167], v[188:191], v[14:17]
	v_mfma_f32_16x16x32_bf16 v[70:73], v[156:159], v[204:207], v[70:73]
	v_mfma_f32_16x16x32_bf16 v[6:9], v[164:167], v[204:207], v[6:9]
	s_barrier
; #define PG8_STAGE(bufoff, gbase, voff) do { _Pragma("unroll") for (int _i = 0; _i < 2; ++_i) \
;         __builtin_amdgcn_global_load_lds((const unsigned*)((const char*)(gbase) + (voff)[_i]), (PG8_LAS unsigned*)(lds + (bufoff) + ldsw + _i * 8192), 16, 0, 0); } while (0)
; #define PG8_LDA(dst, b, h) do { _Pragma("unroll") for (int m = 0; m < 4; ++m) _Pragma("unroll") for (int k = 0; k < 2; ++k) dst[m][k] = *(const PG8_LAS bf16x8*)(lds + PG8_SA(b, h) + aoff + m * 2048 + k * 1024); } while (0)
; #define PG8_LDB(dst, b, h) do { _Pragma("unroll") for (int n = 0; n < 2; ++n) _Pragma("unroll") for (int k = 0; k < 2; ++k) dst[n][k] = *(const PG8_LAS bf16x8*)(lds + PG8_SB(b, h) + boff + n * 2048 + k * 1024); } while (0)
; #define PG8_MMA(ai, bj, At, Bt) do { __builtin_amdgcn_s_setprio(1); _Pragma("unroll") for (int m = 0; m < 4; ++m) _Pragma("unroll") for (int n = 0; n < 2; ++n) _Pragma("unroll") for (int k = 0; k < 2; ++k) \
;         acc[ai][bj][m][n] = __builtin_amdgcn_mfma_f32_16x16x32_bf16(Bt[n][k], At[m][k], acc[ai][bj][m][n], 0, 0, 0); __builtin_amdgcn_s_setprio(0); } while (0)
; #define PG8_WAIT_V(n) asm volatile("s_waitcnt vmcnt(" #n ")" ::: "memory")
; #define PG8_WAIT_L(n) asm volatile("s_waitcnt lgkmcnt(" #n ")" ::: "memory")
; #define PG8_BAR __builtin_amdgcn_s_barrier()
; #define PG8_SCHED __builtin_amdgcn_sched_barrier(0)
; template <class Epi, class Sched, bool ALIGN_EPI = false, bool SP2 = false>
; __device__ __forceinline__ void gemm_phase(PG8_LAS unsigned char* lds, const Gemm g, const Sched& S, const Epi& E) {
;     ...
;             PG8_LDB(B0, 1, 0); PG8_LDB(B1, 1, 1); PG8_SCHED; PG8_LDA(At, 1, 0); PG8_STAGE(PG8_SA(0, 1), a2 + hstep, voffA);
;             PG8_WAIT_V(8); PG8_WAIT_L(0); PG8_BAR; PG8_MMA(0, 0, At, B0); PG8_MMA(0, 1, At, B1); PG8_BAR; PG8_SCHED;
;             PG8_LDA(At, 1, 1); PG8_STAGE(PG8_SB(1, 0), b3, voffB); PG8_STAGE(PG8_SB(1, 1), b3 + hstep, voffB); PG8_STAGE(PG8_SA(1, 0), a3, voffA);
;             PG8_WAIT_V(8); PG8_WAIT_L(0); PG8_BAR; PG8_MMA(1, 0, At, B0); PG8_MMA(1, 1, At, B1); PG8_BAR; PG8_SCHED;
	s_setprio 0
	s_add_i32 s84, 0, 0x18000
	s_add_i32 s85, 0, 0x1c000
	ds_read_b128 v[114:117], v218 offset:32768
	ds_read_b128 v[118:121], v218 offset:33792
	ds_read_b128 v[130:133], v218 offset:34816
	ds_read_b128 v[138:141], v218 offset:35840
	ds_read_b128 v[146:149], v218 offset:49152
	ds_read_b128 v[156:159], v218 offset:50176
	ds_read_b128 v[160:163], v218 offset:51200
	ds_read_b128 v[164:167], v218 offset:52224
	s_add_u32 s68, s68, 0x80000
	s_addc_u32 s69, s69, 0
	s_mov_b32 m0, s5
	ds_read_b128 v[168:171], v199 offset:32768
	ds_read_b128 v[172:175], v199 offset:33792
	ds_read_b128 v[176:179], v199 offset:34816
	ds_read_b128 v[180:183], v199 offset:35840
	ds_read_b128 v[184:187], v199 offset:36864
	ds_read_b128 v[188:191], v199 offset:37888
	ds_read_b128 v[200:203], v199 offset:38912
	ds_read_b128 v[204:207], v199 offset:39936
	global_load_lds_dwordx4 v0, s[68:69]
	s_mov_b32 m0, s6
	s_nop 0
	global_load_lds_dwordx4 v150, s[68:69]
	s_waitcnt vmcnt(8) lgkmcnt(0)
	s_setprio 1
	s_barrier
	v_mfma_f32_16x16x32_bf16 v[142:145], v[114:117], v[168:171], v[142:145]
	v_mfma_f32_16x16x32_bf16 v[62:65], v[130:133], v[168:171], v[62:65]
	v_mfma_f32_16x16x32_bf16 v[122:125], v[114:117], v[176:179], v[122:125]
	v_mfma_f32_16x16x32_bf16 v[50:53], v[130:133], v[176:179], v[50:53]
	v_mfma_f32_16x16x32_bf16 v[106:109], v[114:117], v[184:187], v[106:109]
	v_mfma_f32_16x16x32_bf16 v[42:45], v[130:133], v[184:187], v[42:45]
	v_mfma_f32_16x16x32_bf16 v[98:101], v[114:117], v[200:203], v[98:101]
	v_mfma_f32_16x16x32_bf16 v[34:37], v[130:133], v[200:203], v[34:37]
	v_mfma_f32_16x16x32_bf16 v[142:145], v[118:121], v[172:175], v[142:145]
	v_mfma_f32_16x16x32_bf16 v[62:65], v[138:141], v[172:175], v[62:65]
	v_mfma_f32_16x16x32_bf16 v[122:125], v[118:121], v[180:183], v[122:125]
	v_mfma_f32_16x16x32_bf16 v[50:53], v[138:141], v[180:183], v[50:53]
	v_mfma_f32_16x16x32_bf16 v[106:109], v[118:121], v[188:191], v[106:109]
	v_mfma_f32_16x16x32_bf16 v[42:45], v[138:141], v[188:191], v[42:45]
	v_mfma_f32_16x16x32_bf16 v[98:101], v[118:121], v[204:207], v[98:101]
	v_mfma_f32_16x16x32_bf16 v[34:37], v[138:141], v[204:207], v[34:37]
	v_mfma_f32_16x16x32_bf16 v[134:137], v[146:149], v[168:171], v[134:137]
	v_mfma_f32_16x16x32_bf16 v[58:61], v[160:163], v[168:171], v[58:61]
	v_mfma_f32_16x16x32_bf16 v[126:129], v[146:149], v[176:179], v[126:129]
	v_mfma_f32_16x16x32_bf16 v[54:57], v[160:163], v[176:179], v[54:57]
	v_mfma_f32_16x16x32_bf16 v[110:113], v[146:149], v[184:187], v[110:113]
	v_mfma_f32_16x16x32_bf16 v[46:49], v[160:163], v[184:187], v[46:49]
	v_mfma_f32_16x16x32_bf16 v[102:105], v[146:149], v[200:203], v[102:105]
	v_mfma_f32_16x16x32_bf16 v[38:41], v[160:163], v[200:203], v[38:41]
	v_mfma_f32_16x16x32_bf16 v[134:137], v[156:159], v[172:175], v[134:137]
	v_mfma_f32_16x16x32_bf16 v[58:61], v[164:167], v[172:175], v[58:61]
	v_mfma_f32_16x16x32_bf16 v[126:129], v[156:159], v[180:183], v[126:129]
	v_mfma_f32_16x16x32_bf16 v[54:57], v[164:167], v[180:183], v[54:57]
	v_mfma_f32_16x16x32_bf16 v[110:113], v[156:159], v[188:191], v[110:113]
	v_mfma_f32_16x16x32_bf16 v[46:49], v[164:167], v[188:191], v[46:49]
	v_mfma_f32_16x16x32_bf16 v[102:105], v[156:159], v[204:207], v[102:105]
	v_mfma_f32_16x16x32_bf16 v[38:41], v[164:167], v[204:207], v[38:41]
	s_barrier
	s_setprio 0
	s_add_i32 s68, s84, s1
	s_mov_b32 m0, s68
	ds_read_b128 v[168:171], v199 offset:49152
	ds_read_b128 v[172:175], v199 offset:50176
	ds_read_b128 v[176:179], v199 offset:51200
	ds_read_b128 v[180:183], v199 offset:52224
	ds_read_b128 v[184:187], v199 offset:53248
	ds_read_b128 v[188:191], v199 offset:54272
	ds_read_b128 v[200:203], v199 offset:55296
	ds_read_b128 v[204:207], v199 offset:56320
	global_load_lds_dwordx4 v0, s[100:101]
	s_add_i32 m0, s68, 0x2000
	s_add_i32 s68, s85, s1
	global_load_lds_dwordx4 v150, s[100:101]
	s_add_u32 s10, s10, 0x80080
	s_addc_u32 s11, s11, 0
	s_mov_b32 m0, s68
	s_nop 0
	global_load_lds_dwordx4 v0, s[10:11]
	s_add_i32 m0, s68, 0x2000
	s_nop 0
	global_load_lds_dwordx4 v150, s[10:11]
	s_mov_b32 m0, s7
	s_nop 0
	global_load_lds_dwordx4 v0, s[98:99]
	s_mov_b32 m0, s30
	s_nop 0
	global_load_lds_dwordx4 v150, s[98:99]
	s_waitcnt vmcnt(8) lgkmcnt(0)
	s_setprio 1
	s_barrier
	v_mfma_f32_16x16x32_bf16 v[94:97], v[114:117], v[168:171], v[94:97]
	v_mfma_f32_16x16x32_bf16 v[30:33], v[130:133], v[168:171], v[30:33]
	v_mfma_f32_16x16x32_bf16 v[82:85], v[114:117], v[176:179], v[82:85]
	v_mfma_f32_16x16x32_bf16 v[18:21], v[130:133], v[176:179], v[18:21]
	v_mfma_f32_16x16x32_bf16 v[74:77], v[114:117], v[184:187], v[74:77]
	v_mfma_f32_16x16x32_bf16 v[10:13], v[130:133], v[184:187], v[10:13]
	v_mfma_f32_16x16x32_bf16 v[66:69], v[114:117], v[200:203], v[66:69]
	v_mfma_f32_16x16x32_bf16 v[2:5], v[130:133], v[200:203], v[2:5]
	v_mfma_f32_16x16x32_bf16 v[94:97], v[118:121], v[172:175], v[94:97]
	v_mfma_f32_16x16x32_bf16 v[30:33], v[138:141], v[172:175], v[30:33]
	v_mfma_f32_16x16x32_bf16 v[82:85], v[118:121], v[180:183], v[82:85]
	v_mfma_f32_16x16x32_bf16 v[18:21], v[138:141], v[180:183], v[18:21]
	v_mfma_f32_16x16x32_bf16 v[74:77], v[118:121], v[188:191], v[74:77]
	v_mfma_f32_16x16x32_bf16 v[10:13], v[138:141], v[188:191], v[10:13]
	v_mfma_f32_16x16x32_bf16 v[66:69], v[118:121], v[204:207], v[66:69]
	v_mfma_f32_16x16x32_bf16 v[2:5], v[138:141], v[204:207], v[2:5]
	v_mfma_f32_16x16x32_bf16 v[90:93], v[146:149], v[168:171], v[90:93]
	v_mfma_f32_16x16x32_bf16 v[26:29], v[160:163], v[168:171], v[26:29]
	v_mfma_f32_16x16x32_bf16 v[86:89], v[146:149], v[176:179], v[86:89]
	v_mfma_f32_16x16x32_bf16 v[22:25], v[160:163], v[176:179], v[22:25]
	v_mfma_f32_16x16x32_bf16 v[78:81], v[146:149], v[184:187], v[78:81]
	v_mfma_f32_16x16x32_bf16 v[14:17], v[160:163], v[184:187], v[14:17]
	v_mfma_f32_16x16x32_bf16 v[70:73], v[146:149], v[200:203], v[70:73]
	v_mfma_f32_16x16x32_bf16 v[6:9], v[160:163], v[200:203], v[6:9]
	v_mfma_f32_16x16x32_bf16 v[90:93], v[156:159], v[172:175], v[90:93]
	v_mfma_f32_16x16x32_bf16 v[26:29], v[164:167], v[172:175], v[26:29]
	v_mfma_f32_16x16x32_bf16 v[86:89], v[156:159], v[180:183], v[86:89]
	v_mfma_f32_16x16x32_bf16 v[22:25], v[164:167], v[180:183], v[22:25]
	v_mfma_f32_16x16x32_bf16 v[78:81], v[156:159], v[188:191], v[78:81]
	v_mfma_f32_16x16x32_bf16 v[14:17], v[164:167], v[188:191], v[14:17]
	v_mfma_f32_16x16x32_bf16 v[70:73], v[156:159], v[204:207], v[70:73]
	v_mfma_f32_16x16x32_bf16 v[6:9], v[164:167], v[204:207], v[6:9]
	s_barrier
	s_setprio 0
	s_add_i32 s13, s13, 2
	s_add_u32 vcc_lo, vcc_lo, 0x100
	s_addc_u32 vcc_hi, vcc_hi, 0
	s_add_u32 s21, s21, 0x100
	s_addc_u32 s12, s12, 0
	s_cmp_gt_u32 s13, 29
	s_cbranch_scc0 .LBB0_38
	s_and_b64 vcc, exec, s[58:59]
	s_cbranch_vccz .LBB0_41
;     __device__ __forceinline__ void operator()(const f32x4 (&acc)[2][2][4][2], const Unit& u, int wr, int wc, int fr, int fq) const {
;         constexpr int FF = 5504;
;         const int lane = otid() & 63;
;         const int src1 = (lane & 48) | ((fr + 15) & 15), src2 = (lane & 48) | ((fr + 14) & 15);
;         float rs[2][4];
; #pragma unroll
;         for (int ai = 0; ai < 2; ++ai)
; #pragma unroll
;             for (int m = 0; m < 4; ++m) rs[ai][m] = __builtin_amdgcn_rsqf((float)ss[u.pm * BM + ai * HALF + wr * 64 + m * 16 + fr] * (1.f / (2048.f * 262144.f)) + 1e-6f);
; #pragma unroll
;         for (int n = 0; n < 2; ++n) {
;             const int cbase = 128 * u.pn + 32 * wc + 16 * n + 4 * fq;
;             const f32x4 w0 = *(const f32x4*)(cw + cbase), w1 = *(const f32x4*)(cw + FF + cbase), w2 = *(const f32x4*)(cw + 2 * FF + cbase), b4 = *(const f32x4*)(cb + cbase);
; #pragma unroll
;             for (int ai = 0; ai < 2; ++ai) {
;                 const int slab = u.pm * 4 + 2 * ai + wr;
;                 f32x4 r1p = (f32x4){0.f, 0.f, 0.f, 0.f}, r2p = (f32x4){0.f, 0.f, 0.f, 0.f};
; #pragma unroll
;                 for (int m = 0; m < 4; ++m) {
;                     const f32x4 g = acc[ai][1][m][n] * rs[ai][m], v = acc[ai][0][m][n] * rs[ai][m];
;                     f32x4 r1, r2, a;
; #pragma unroll
;                     for (int e = 0; e < 4; ++e) { r1[e] = __shfl(g[e], src1); r2[e] = __shfl(g[e], src2); }
; #pragma unroll
;                     for (int e = 0; e < 4; ++e) {
;                         const float p1 = fr >= 1 ? r1[e] : r1p[e], p2 = fr >= 2 ? r2[e] : r2p[e];
;                         const float gg = b4[e] + w0[e] * p2 + w1[e] * p1 + w2[e] * g[e];
;                         a[e] = gg * __builtin_amdgcn_rcpf(1.f + __expf(-gg)) * v[e];
;                     }
;                     r1p = r1; r2p = r2;
;                     const size_t row = (size_t)(u.pm * BM + ai * HALF + wr * 64 + m * 16 + fr);
;                     if (m == 0 && fr < 2) {
;                         *(f32x4*)(GF + (size_t)(slab * 2 + fr) * FF + cbase) = g; *(f32x4*)(VF + (size_t)(slab * 2 + fr) * FF + cbase) = v;
;                     } else {
;                         typedef unsigned u32x2v __attribute__((ext_vector_type(2)));
;                         u32x2v w; w.x = cvt_pk_bf16(a[0], a[1]); w.y = cvt_pk_bf16(a[2], a[3]);
.LBB0_41:
	v_lshl_add_u32 v160, s66, 8, v193
	v_ashrrev_i32_e32 v161, 31, v160
	v_mov_b32_e32 v148, v227
	v_bfe_u32 v205, v227, 4, 1
	v_mul_u32_u24_e32 v205, 24, v205
	s_and_b32 s98, s65, 1
	s_lshl_b32 s98, s98, 12
	s_add_i32 s98, s98, 0x20000
	s_add_i32 s99, s98, 0x800
	v_lshl_add_u32 v114, v193, 3, s98
	ds_read_b64 v[146:147], v114
	v_lshl_or_b32 v156, s64, 7, v198
	v_ashrrev_i32_e32 v157, 31, v156
	ds_read_b64 v[190:191], v114 offset:128
	ds_read_b64 v[188:189], v114 offset:256
	ds_read_b64 v[186:187], v114 offset:384
	ds_read_b64 v[176:177], v114 offset:1024
	ds_read_b64 v[174:175], v114 offset:1152
	ds_read_b64 v[172:173], v114 offset:1280
	ds_read_b64 v[170:171], v114 offset:1408
	v_lshlrev_b64 v[158:159], 2, v[156:157]
	v_lshl_add_u32 v166, v198, 2, s99
	v_lshl_add_u64 v[118:119], s[60:61], 0, v[158:159]
	v_lshl_add_u64 v[120:121], s[62:63], 0, v[158:159]
	v_lshl_add_u64 v[164:165], s[54:55], 0, v[158:159]
	ds_read_b128 v[114:117], v166
	ds_read_b128 v[138:141], v166 offset:512
	ds_read_b128 v[130:133], v166 offset:1024
	s_nop 0
	ds_read_b128 v[118:121], v166 offset:1536
	s_waitcnt lgkmcnt(0)
	v_ffbh_u32_e32 v149, v147
	v_min_u32_e32 v149, 32, v149
	v_lshlrev_b64 v[146:147], v149, v[146:147]
	v_min_u32_e32 v146, 1, v146
	v_or_b32_e32 v146, v147, v146
	v_cvt_f32_u32_e32 v146, v146
	v_sub_u32_e32 v149, 32, v149
	v_and_b32_e32 v147, 48, v148
	v_or3_b32 v148, v147, v195, v236
	v_ldexp_f32 v146, v146, v149
	v_fmamk_f32 v146, v146, 0x31000000, v232
	v_rsq_f32_e32 v162, v146
	v_or3_b32 v146, v147, v196, v236
	v_lshlrev_b32_e32 v200, 2, v146
	v_lshlrev_b32_e32 v161, 2, v148
	v_pk_mul_f32 v[146:147], v[134:135], v[162:163] op_sel_hi:[1,0]
	v_pk_mul_f32 v[148:149], v[136:137], v[162:163] op_sel_hi:[1,0]
	s_nop 1
	v_mov_b32_dpp v163, v146 row_ror:2 row_mask:0xf bank_mask:0xf
	v_mov_b32_dpp v179, v146 row_ror:1 row_mask:0xf bank_mask:0xf
	v_mov_b32_dpp v181, v147 row_ror:1 row_mask:0xf bank_mask:0xf
	v_mov_b32_dpp v201, v147 row_ror:2 row_mask:0xf bank_mask:0xf
	v_mov_b32_dpp v183, v148 row_ror:1 row_mask:0xf bank_mask:0xf
	v_mov_b32_dpp v202, v148 row_ror:2 row_mask:0xf bank_mask:0xf
	v_mov_b32_dpp v185, v149 row_ror:1 row_mask:0xf bank_mask:0xf
	v_mov_b32_dpp v203, v149 row_ror:2 row_mask:0xf bank_mask:0xf
	s_waitcnt lgkmcnt(7)
	v_pk_mul_f32 v[136:137], v[144:145], v[162:163] op_sel_hi:[1,0]
	v_pk_mul_f32 v[134:135], v[142:143], v[162:163] op_sel_hi:[1,0]
	s_and_saveexec_b64 s[10:11], s[42:43]
	s_xor_b64 s[10:11], exec, s[10:11]
	s_movk_i32 s17, 0x2b00
	s_movk_i32 s84, 0x300
	s_mov_b32 s86, 0x24000
	s_mov_b32 s88, 0x48800000
	s_cbranch_execz .LBB0_43
	v_mov_b32_e32 v142, v149
	v_mov_b32_e32 v143, v141
	v_mov_b32_e32 v184, v133
	s_waitcnt lgkmcnt(1)
	v_pk_mul_f32 v[142:143], v[142:143], v[184:185]
	s_waitcnt lgkmcnt(0)
	v_fma_f32 v144, v117, v203, v121
	v_add_f32_e32 v143, v143, v144
	v_add_f32_e32 v142, v142, v143
	v_mul_f32_e32 v143, 0xbfb8aa3b, v142
	v_exp_f32_e32 v143, v143
	v_mov_b32_e32 v149, v140
	v_mov_b32_e32 v182, v132
	v_mov_b32_e32 v180, v131
	v_add_f32_e32 v143, 1.0, v143
	v_rcp_f32_e32 v143, v143
	v_mov_b32_e32 v178, v130
	v_mul_f32_e32 v142, v142, v143
	v_mul_f32_e32 v144, v137, v142
	v_pk_mul_f32 v[142:143], v[148:149], v[182:183]
	v_fma_f32 v137, v116, v202, v120
	v_add_f32_e32 v137, v143, v137
	v_add_f32_e32 v137, v142, v137
	v_mul_f32_e32 v142, 0xbfb8aa3b, v137
	v_exp_f32_e32 v142, v142
	v_fma_f32 v143, v115, v201, v119
	v_add_f32_e32 v142, 1.0, v142
	v_rcp_f32_e32 v142, v142
	s_nop 0
	v_mul_f32_e32 v137, v137, v142
	v_mul_f32_e32 v142, v136, v137
	v_mov_b32_e32 v136, v147
	v_mov_b32_e32 v137, v139
	v_pk_mul_f32 v[136:137], v[136:137], v[180:181]
	v_mov_b32_e32 v147, v138
	v_add_f32_e32 v137, v137, v143
	v_add_f32_e32 v136, v136, v137
	v_mul_f32_e32 v137, 0xbfb8aa3b, v136
	v_exp_f32_e32 v137, v137
	v_fma_f32 v143, v114, v163, v118
	v_add_f32_e32 v137, 1.0, v137
	v_rcp_f32_e32 v137, v137
	s_nop 0
	v_mul_f32_e32 v136, v136, v137
	v_mul_f32_e32 v135, v135, v136
	v_pk_mul_f32 v[136:137], v[146:147], v[178:179]
	s_nop 0
	v_add_f32_e32 v137, v137, v143
	v_add_f32_e32 v136, v136, v137
	v_mul_f32_e32 v137, 0xbfb8aa3b, v136
	v_exp_f32_e32 v137, v137
	s_nop 0
	v_add_f32_e32 v137, 1.0, v137
	v_rcp_f32_e32 v137, v137
	s_nop 0
	v_mul_f32_e32 v136, v136, v137
	v_mul_f32_e32 v134, v134, v136
	v_mov_b64_e32 v[136:137], s[48:49]
	v_mad_i64_i32 v[136:137], s[12:13], v160, s17, v[136:137]
	v_cvt_pk_bf16_f32 v134, v134, v135
	v_cvt_pk_bf16_f32 v135, v142, v144
	v_lshl_add_u64 v[136:137], v[156:157], 1, v[136:137]
	v_mov_b32_e32 v220, v134
	v_mov_b32_e32 v221, v135

; __device__ __forceinline__ unsigned cvt_pk_bf16(float lo, float hi) { unsigned r; asm volatile("v_cvt_pk_bf16_f32 %0, %1, %2" : "=v"(r) : "v"(lo), "v"(hi)); return r; }
;     __device__ __forceinline__ void operator()(const f32x4 (&acc)[2][2][4][2], const Unit& u, int wr, int wc, int fr, int fq) const {
;     ...
;             for (int m = 0; m < 4; ++m) rs[ai][m] = __builtin_amdgcn_rsqf((float)ss[u.pm * BM + ai * HALF + wr * 64 + m * 16 + fr] * (1.f / (2048.f * 262144.f)) + 1e-6f);
; #pragma unroll
;         for (int n = 0; n < 2; ++n) {
;             const int cbase = 128 * u.pn + 32 * wc + 16 * n + 4 * fq;
;             const f32x4 w0 = *(const f32x4*)(cw + cbase), w1 = *(const f32x4*)(cw + FF + cbase), w2 = *(const f32x4*)(cw + 2 * FF + cbase), b4 = *(const f32x4*)(cb + cbase);
; #pragma unroll
;             for (int ai = 0; ai < 2; ++ai) {
;                 const int slab = u.pm * 4 + 2 * ai + wr;
;                 f32x4 r1p = (f32x4){0.f, 0.f, 0.f, 0.f}, r2p = (f32x4){0.f, 0.f, 0.f, 0.f};
; #pragma unroll
;                 for (int m = 0; m < 4; ++m) {
;                     const f32x4 g = acc[ai][1][m][n] * rs[ai][m], v = acc[ai][0][m][n] * rs[ai][m];
;                     f32x4 r1, r2, a;
; #pragma unroll
;                     for (int e = 0; e < 4; ++e) { r1[e] = __shfl(g[e], src1); r2[e] = __shfl(g[e], src2); }
; #pragma unroll
;                     for (int e = 0; e < 4; ++e) {
;                         const float p1 = fr >= 1 ? r1[e] : r1p[e], p2 = fr >= 2 ? r2[e] : r2p[e];
;                         const float gg = b4[e] + w0[e] * p2 + w1[e] * p1 + w2[e] * g[e];
;                         a[e] = gg * __builtin_amdgcn_rcpf(1.f + __expf(-gg)) * v[e];
;                     }
;                     r1p = r1; r2p = r2;
;                     const size_t row = (size_t)(u.pm * BM + ai * HALF + wr * 64 + m * 16 + fr);
;                     if (m == 0 && fr < 2) {
;                         *(f32x4*)(GF + (size_t)(slab * 2 + fr) * FF + cbase) = g; *(f32x4*)(VF + (size_t)(slab * 2 + fr) * FF + cbase) = v;
;                     } else {
;                         typedef unsigned u32x2v __attribute__((ext_vector_type(2)));
;                         u32x2v w; w.x = cvt_pk_bf16(a[0], a[1]); w.y = cvt_pk_bf16(a[2], a[3]);
;                         *(u32x2v*)(ACT + row * FF + cbase) = w;
;                     }
.LBB0_45:
	s_or_b64 exec, exec, s[10:11]
	s_and_b64 vcc, exec, s[58:59]
	s_cbranch_vccz .Lalign_up
	s_barrier
.Lalign_up:
	s_nop 0
	v_ffbh_u32_e32 v134, v191
	v_min_u32_e32 v136, 32, v134
	v_lshlrev_b64 v[134:135], v136, v[190:191]
	v_min_u32_e32 v134, 1, v134
	v_or_b32_e32 v134, v135, v134
	v_cvt_f32_u32_e32 v134, v134
	v_ffbh_u32_e32 v135, v189
	v_sub_u32_e32 v136, 32, v136
	v_min_u32_e32 v143, 32, v135
	v_ldexp_f32 v134, v134, v136
	v_fmamk_f32 v136, v134, 0x31000000, v232
	v_lshlrev_b64 v[134:135], v143, v[188:189]
	v_min_u32_e32 v134, 1, v134
	v_or_b32_e32 v134, v135, v134
	v_cvt_f32_u32_e32 v134, v134
	v_sub_u32_e32 v135, 32, v143
	v_rsq_f32_e32 v142, v136
	v_mov_b32_e32 v149, v141
	v_ldexp_f32 v134, v134, v135
	v_fmamk_f32 v136, v134, 0x31000000, v232
	v_ffbh_u32_e32 v134, v187
	v_min_u32_e32 v143, 32, v134
	v_lshlrev_b64 v[134:135], v143, v[186:187]
	v_min_u32_e32 v134, 1, v134
	v_or_b32_e32 v134, v135, v134
	v_cvt_f32_u32_e32 v134, v134
	v_sub_u32_e32 v143, 32, v143
	s_movk_i32 s10, 0x5600
	v_rsq_f32_e32 v136, v136
	v_ldexp_f32 v134, v134, v143
	v_add_u32_e32 v143, s12, v197
	v_pk_mul_f32 v[128:129], v[128:129], v[142:143] op_sel_hi:[1,0]
	s_nop 1
	v_mov_b32_dpp v186, v129 row_ror:1 row_mask:0xf bank_mask:0xf
	v_mov_b32_dpp v191, v129 row_ror:2 row_mask:0xf bank_mask:0xf
	v_mov_b32_e32 v148, v129
	v_pk_mul_f32 v[126:127], v[126:127], v[142:143] op_sel_hi:[1,0]
	v_mad_i64_i32 v[146:147], s[10:11], v143, s10, 0
	s_waitcnt lgkmcnt(1)
	v_cndmask_b32_e64 v185, v186, v185, s[40:41]
	s_waitcnt lgkmcnt(0)
	v_cndmask_b32_e64 v129, v203, v191, s[42:43]
	v_pk_mul_f32 v[148:149], v[148:149], v[184:185]
	v_fma_f32 v129, v117, v129, v121
	v_add_f32_e32 v129, v149, v129
	v_add_f32_e32 v148, v148, v129
	v_mul_f32_e32 v129, 0xbfb8aa3b, v148
	v_exp_f32_e32 v129, v129
	v_mov_b32_dpp v149, v128 row_ror:1 row_mask:0xf bank_mask:0xf
	v_mov_b32_dpp v203, v128 row_ror:2 row_mask:0xf bank_mask:0xf
	v_mov_b32_dpp v143, v126 row_ror:1 row_mask:0xf bank_mask:0xf
	v_add_f32_e32 v129, 1.0, v129
	v_rcp_f32_e32 v185, v129
	s_waitcnt lgkmcnt(2)
	v_cndmask_b32_e64 v183, v149, v183, s[40:41]
	v_mov_b32_e32 v129, v140
	v_pk_mul_f32 v[128:129], v[128:129], v[182:183]
	s_waitcnt lgkmcnt(1)
	v_cndmask_b32_e64 v183, v202, v203, s[42:43]
	v_fma_f32 v183, v116, v183, v120
	v_add_f32_e32 v129, v129, v183
	v_add_f32_e32 v183, v128, v129
	v_mul_f32_e32 v128, 0xbfb8aa3b, v183
	v_mov_b32_dpp v189, v127 row_ror:1 row_mask:0xf bank_mask:0xf
	v_mov_b32_dpp v190, v127 row_ror:2 row_mask:0xf bank_mask:0xf
	v_exp_f32_e32 v128, v128
	s_waitcnt lgkmcnt(2)
	v_pk_mul_f32 v[124:125], v[124:125], v[142:143] op_sel_hi:[1,0]
	v_mul_f32_e32 v129, v148, v185
	v_mov_b32_dpp v187, v126 row_ror:2 row_mask:0xf bank_mask:0xf
	v_add_f32_e32 v128, 1.0, v128
	v_mul_f32_e32 v125, v125, v129
	v_rcp_f32_e32 v148, v128
	s_waitcnt lgkmcnt(2)
	v_cndmask_b32_e64 v181, v189, v181, s[40:41]
	v_mov_b32_e32 v128, v127
	v_mov_b32_e32 v129, v139
	s_waitcnt lgkmcnt(1)
	v_cndmask_b32_e64 v127, v201, v190, s[42:43]
	v_pk_mul_f32 v[128:129], v[128:129], v[180:181]
	v_fma_f32 v127, v115, v127, v119
	v_add_f32_e32 v127, v129, v127
	v_add_f32_e32 v128, v128, v127
	v_mul_f32_e32 v127, 0xbfb8aa3b, v128
	v_exp_f32_e32 v129, v127
	v_cndmask_b32_e64 v179, v143, v179, s[40:41]
	v_mov_b32_e32 v127, v138
	s_waitcnt lgkmcnt(0)
	v_cndmask_b32_e64 v163, v163, v187, s[42:43]
	v_pk_mul_f32 v[126:127], v[126:127], v[178:179]
	v_fma_f32 v163, v114, v163, v118
	v_add_f32_e32 v127, v127, v163
	v_add_f32_e32 v126, v126, v127
	v_mul_f32_e32 v127, 0xbfb8aa3b, v126
	v_exp_f32_e32 v127, v127
	v_add_f32_e32 v129, 1.0, v129
	v_rcp_f32_e32 v129, v129
	v_or_b32_e32 v137, 16, v160
	v_add_f32_e32 v127, 1.0, v127
	v_rcp_f32_e32 v127, v127
	v_mul_f32_e32 v148, v183, v148
	v_pk_mul_f32 v[112:113], v[112:113], v[136:137] op_sel_hi:[1,0]
	v_mul_f32_e32 v124, v124, v148
	s_nop 1
	v_mov_b32_dpp v148, v113 row_ror:1 row_mask:0xf bank_mask:0xf
	v_mov_b32_dpp v204, v113 row_ror:2 row_mask:0xf bank_mask:0xf
	v_pk_mul_f32 v[122:123], v[122:123], v[142:143] op_sel_hi:[1,0]
	v_mul_f32_e32 v128, v128, v129
	v_mul_f32_e32 v126, v126, v127
	v_mul_f32_e32 v123, v123, v128
	v_mul_f32_e32 v122, v122, v126
	v_mov_b64_e32 v[128:129], s[48:49]
	v_cvt_pk_bf16_f32 v126, v122, v123
	v_cvt_pk_bf16_f32 v127, v124, v125
	v_mad_i64_i32 v[122:123], s[10:11], v137, s17, v[128:129]
	v_lshlrev_b64 v[124:125], 1, v[156:157]
	v_lshl_add_u64 v[122:123], v[122:123], 0, v[124:125]
	v_mov_b32_e32 v206, v126
	v_mov_b32_e32 v207, v127
	s_waitcnt lgkmcnt(1)
	v_cndmask_b32_e64 v185, v148, v186, s[40:41]
	v_mov_b32_e32 v126, v113
	v_mov_b32_e32 v127, v141
	s_waitcnt lgkmcnt(0)
	v_cndmask_b32_e64 v113, v191, v204, s[42:43]
	v_pk_mul_f32 v[126:127], v[126:127], v[184:185]
	v_fma_f32 v113, v117, v113, v121
	v_add_f32_e32 v113, v127, v113
	v_add_f32_e32 v126, v126, v113
	v_mul_f32_e32 v113, 0xbfb8aa3b, v126
	v_exp_f32_e32 v113, v113
	v_mov_b32_dpp v127, v112 row_ror:1 row_mask:0xf bank_mask:0xf
	v_mov_b32_dpp v186, v112 row_ror:2 row_mask:0xf bank_mask:0xf
	v_pk_mul_f32 v[110:111], v[110:111], v[136:137] op_sel_hi:[1,0]
	v_add_f32_e32 v113, 1.0, v113
	v_rcp_f32_e32 v179, v113
	s_waitcnt lgkmcnt(1)
	v_cndmask_b32_e64 v183, v127, v149, s[40:41]
	v_mov_b32_e32 v113, v140
	s_waitcnt lgkmcnt(0)
; __device__ __forceinline__ unsigned cvt_pk_bf16(float lo, float hi) { unsigned r; asm volatile("v_cvt_pk_bf16_f32 %0, %1, %2" : "=v"(r) : "v"(lo), "v"(hi)); return r; }
;     __device__ __forceinline__ void operator()(const f32x4 (&acc)[2][2][4][2], const Unit& u, int wr, int wc, int fr, int fq) const {
;     ...
;                 for (int m = 0; m < 4; ++m) {
;                     const f32x4 g = acc[ai][1][m][n] * rs[ai][m], v = acc[ai][0][m][n] * rs[ai][m];
;                     f32x4 r1, r2, a;
; #pragma unroll
;                     for (int e = 0; e < 4; ++e) { r1[e] = __shfl(g[e], src1); r2[e] = __shfl(g[e], src2); }
; #pragma unroll
;                     for (int e = 0; e < 4; ++e) {
;                         const float p1 = fr >= 1 ? r1[e] : r1p[e], p2 = fr >= 2 ? r2[e] : r2p[e];
;                         const float gg = b4[e] + w0[e] * p2 + w1[e] * p1 + w2[e] * g[e];
;                         a[e] = gg * __builtin_amdgcn_rcpf(1.f + __expf(-gg)) * v[e];
;                     }
;                     r1p = r1; r2p = r2;
;                     const size_t row = (size_t)(u.pm * BM + ai * HALF + wr * 64 + m * 16 + fr);
;                     if (m == 0 && fr < 2) {
;                         *(f32x4*)(GF + (size_t)(slab * 2 + fr) * FF + cbase) = g; *(f32x4*)(VF + (size_t)(slab * 2 + fr) * FF + cbase) = v;
;                     } else {
;                         typedef unsigned u32x2v __attribute__((ext_vector_type(2)));
;                         u32x2v w; w.x = cvt_pk_bf16(a[0], a[1]); w.y = cvt_pk_bf16(a[2], a[3]);
;                         *(u32x2v*)(ACT + row * FF + cbase) = w;
;                     }
;                     if (m == 3 && fr >= 14) *(f32x4*)(GL + (size_t)(slab * 2 + fr - 14) * FF + cbase) = g;
	v_cndmask_b32_e64 v149, v203, v186, s[42:43]
	v_pk_mul_f32 v[112:113], v[112:113], v[182:183]
	v_fma_f32 v149, v116, v149, v120
	v_add_f32_e32 v113, v113, v149
	v_add_f32_e32 v149, v112, v113
	v_mov_b32_dpp v137, v110 row_ror:1 row_mask:0xf bank_mask:0xf
	v_mul_f32_e32 v112, 0xbfb8aa3b, v149
	v_mov_b32_dpp v201, v111 row_ror:1 row_mask:0xf bank_mask:0xf
	v_mov_b32_dpp v202, v111 row_ror:2 row_mask:0xf bank_mask:0xf
	v_exp_f32_e32 v112, v112
	s_waitcnt lgkmcnt(2)
	v_pk_mul_f32 v[108:109], v[108:109], v[136:137] op_sel_hi:[1,0]
	v_mul_f32_e32 v113, v126, v179
	v_mov_b32_dpp v163, v110 row_ror:2 row_mask:0xf bank_mask:0xf
	v_add_f32_e32 v112, 1.0, v112
	v_mul_f32_e32 v109, v109, v113
	v_rcp_f32_e32 v126, v112
	s_waitcnt lgkmcnt(2)
	v_cndmask_b32_e64 v181, v201, v189, s[40:41]
	v_mov_b32_e32 v112, v111
	v_mov_b32_e32 v113, v139
	s_waitcnt lgkmcnt(1)
	v_cndmask_b32_e64 v111, v190, v202, s[42:43]
	v_pk_mul_f32 v[112:113], v[112:113], v[180:181]
	v_fma_f32 v111, v115, v111, v119
	v_add_f32_e32 v111, v113, v111
	v_add_f32_e32 v112, v112, v111
	v_mul_f32_e32 v111, 0xbfb8aa3b, v112
	v_exp_f32_e32 v113, v111
	v_cndmask_b32_e64 v179, v137, v143, s[40:41]
	v_mov_b32_e32 v111, v138
	s_waitcnt lgkmcnt(0)
	v_cndmask_b32_e64 v143, v187, v163, s[42:43]
	v_pk_mul_f32 v[110:111], v[110:111], v[178:179]
	v_fma_f32 v143, v114, v143, v118
	v_add_f32_e32 v111, v111, v143
	v_add_f32_e32 v110, v110, v111
	v_mul_f32_e32 v111, 0xbfb8aa3b, v110
	v_exp_f32_e32 v111, v111
	v_add_f32_e32 v113, 1.0, v113
	v_rcp_f32_e32 v113, v113
	v_fmamk_f32 v134, v134, 0x31000000, v232
	v_add_f32_e32 v111, 1.0, v111
	v_rcp_f32_e32 v111, v111
	v_rsq_f32_e32 v134, v134
	v_pk_mul_f32 v[106:107], v[106:107], v[136:137] op_sel_hi:[1,0]
	v_mul_f32_e32 v126, v149, v126
	v_mul_f32_e32 v112, v112, v113
	v_mul_f32_e32 v110, v110, v111
	v_or_b32_e32 v188, 32, v160
	v_mul_f32_e32 v108, v108, v126
	v_mul_f32_e32 v107, v107, v112
	v_mul_f32_e32 v106, v106, v110
	v_or_b32_e32 v135, 48, v160
	v_cvt_pk_bf16_f32 v106, v106, v107
	v_cvt_pk_bf16_f32 v107, v108, v109
	v_mad_i64_i32 v[108:109], s[10:11], v188, s17, v[128:129]
	v_lshl_add_u64 v[108:109], v[108:109], 0, v[124:125]
	v_pk_mul_f32 v[104:105], v[104:105], v[134:135] op_sel_hi:[1,0]
	v_mov_b32_e32 v208, v106
	v_mov_b32_e32 v209, v107
	v_mov_b32_dpp v106, v105 row_ror:1 row_mask:0xf bank_mask:0xf
	v_mov_b32_dpp v126, v105 row_ror:2 row_mask:0xf bank_mask:0xf
	v_mov_b32_e32 v107, v141
	v_mov_b32_dpp v143, v104 row_ror:2 row_mask:0xf bank_mask:0xf
	v_pk_mul_f32 v[102:103], v[102:103], v[134:135] op_sel_hi:[1,0]
	s_waitcnt lgkmcnt(2)
	v_cndmask_b32_e64 v185, v106, v148, s[40:41]
	v_mov_b32_e32 v106, v105
	s_waitcnt lgkmcnt(1)
	v_cndmask_b32_e64 v126, v204, v126, s[42:43]
	v_pk_mul_f32 v[106:107], v[106:107], v[184:185]
	v_fma_f32 v126, v117, v126, v121
	v_add_f32_e32 v107, v107, v126
	v_add_f32_e32 v126, v106, v107
	v_mul_f32_e32 v106, 0xbfb8aa3b, v126
	v_exp_f32_e32 v106, v106
	v_mov_b32_dpp v107, v104 row_ror:1 row_mask:0xf bank_mask:0xf
	v_mov_b32_dpp v112, v103 row_ror:1 row_mask:0xf bank_mask:0xf
	v_mov_b32_dpp v113, v103 row_ror:2 row_mask:0xf bank_mask:0xf
	v_add_f32_e32 v106, 1.0, v106
	v_rcp_f32_e32 v148, v106
	s_waitcnt lgkmcnt(2)
	v_cndmask_b32_e64 v183, v107, v127, s[40:41]
	v_mov_b32_e32 v106, v104
	v_mov_b32_e32 v107, v140
	v_cndmask_b32_e64 v127, v186, v143, s[42:43]
	v_pk_mul_f32 v[106:107], v[106:107], v[182:183]
	v_fma_f32 v127, v116, v127, v120
	v_add_f32_e32 v107, v107, v127
	v_add_f32_e32 v127, v106, v107
	v_mul_f32_e32 v106, 0xbfb8aa3b, v127
	v_exp_f32_e32 v106, v106
	v_pk_mul_f32 v[100:101], v[100:101], v[134:135] op_sel_hi:[1,0]
	v_mul_f32_e32 v107, v126, v148
	v_mov_b32_dpp v110, v102 row_ror:1 row_mask:0xf bank_mask:0xf
	v_add_f32_e32 v106, 1.0, v106
	v_mov_b32_dpp v111, v102 row_ror:2 row_mask:0xf bank_mask:0xf
	v_mul_f32_e32 v101, v101, v107
	v_rcp_f32_e32 v126, v106
	s_waitcnt lgkmcnt(3)
	v_cndmask_b32_e64 v181, v112, v201, s[40:41]
	v_mov_b32_e32 v106, v103
	v_mov_b32_e32 v107, v139
	s_waitcnt lgkmcnt(2)
	v_cndmask_b32_e64 v112, v202, v113, s[42:43]
	v_pk_mul_f32 v[106:107], v[106:107], v[180:181]
	v_fma_f32 v112, v115, v112, v119
	v_add_f32_e32 v107, v107, v112
	v_add_f32_e32 v112, v106, v107
	v_mul_f32_e32 v106, 0xbfb8aa3b, v112
	v_exp_f32_e32 v113, v106
	s_waitcnt lgkmcnt(1)
	v_cndmask_b32_e64 v179, v110, v137, s[40:41]
	v_mov_b32_e32 v106, v102
	v_mov_b32_e32 v107, v138
	s_waitcnt lgkmcnt(0)
	v_cndmask_b32_e64 v110, v163, v111, s[42:43]
	v_pk_mul_f32 v[106:107], v[106:107], v[178:179]
	v_fma_f32 v110, v114, v110, v118
	v_add_f32_e32 v107, v107, v110
	v_add_f32_e32 v106, v106, v107
	v_mul_f32_e32 v107, 0xbfb8aa3b, v106
	v_exp_f32_e32 v107, v107
	v_add_f32_e32 v111, 1.0, v113
	v_rcp_f32_e32 v111, v111
	v_mul_f32_e32 v110, v127, v126
	v_add_f32_e32 v107, 1.0, v107
	v_rcp_f32_e32 v107, v107
	v_pk_mul_f32 v[98:99], v[98:99], v[134:135] op_sel_hi:[1,0]
	v_mul_f32_e32 v100, v100, v110
	v_mul_f32_e32 v110, v112, v111
	v_mul_f32_e32 v106, v106, v107
	v_mul_f32_e32 v99, v99, v110
	v_mul_f32_e32 v98, v98, v106
	v_cvt_pk_bf16_f32 v98, v98, v99
	v_cvt_pk_bf16_f32 v99, v100, v101
	v_mad_i64_i32 v[100:101], s[10:11], v135, s17, v[128:129]
	v_readlane_b32 s10, v254, 44
	v_lshl_add_u64 v[110:111], v[100:101], 0, v[124:125]
	v_readlane_b32 s11, v254, 45
	v_mov_b32_e32 v210, v98
	v_mov_b32_e32 v211, v99
	s_nop 0
	v_lshl_add_u64 v[98:99], s[10:11], 0, v[146:147]
	v_lshl_add_u64 v[106:107], v[156:157], 2, v[98:99]
	s_and_saveexec_b64 s[10:11], s[44:45]
	v_readlane_b32 s85, v254, 57
	v_readlane_b32 s93, v254, 58
	s_cbranch_execz .LBB0_47
	global_store_dwordx4 v[106:107], v[102:105], off

; __device__ __forceinline__ unsigned cvt_pk_bf16(float lo, float hi) { unsigned r; asm volatile("v_cvt_pk_bf16_f32 %0, %1, %2" : "=v"(r) : "v"(lo), "v"(hi)); return r; }
; #define PG8_BAR __builtin_amdgcn_s_barrier()
;     __device__ __forceinline__ void operator()(const f32x4 (&acc)[2][2][4][2], const Unit& u, int wr, int wc, int fr, int fq) const {
;         const int col0 = u.pn * BM + wc * 32 + 8 * fq;
; #pragma unroll
;         for (int ai = 0; ai < 2; ++ai)
; #pragma unroll
;             for (int m = 0; m < 4; ++m) { const int row = u.pm * BM + ai * HALF + wr * 64 + m * 16 + fr; bf16_t* xp = x + (size_t)row * ldc + col0;
;                 u32x4 bv[2];
; #pragma unroll
;                 for (int bj = 0; bj < 2; ++bj) bv[bj] = *(const u32x4*)(xp + bj * HALF);
;                 float sq = 0.f;
; #pragma unroll
;                 for (int bj = 0; bj < 2; ++bj) { u32x4 w;
; #pragma unroll
;                     for (int n = 0; n < 2; ++n) { const f32x4 a = acc[ai][bj][m][n]; const unsigned b0 = bv[bj][2 * n], b1 = bv[bj][2 * n + 1];
;                         const float o0 = __builtin_bit_cast(float, b0 << 16) + a[0], o1 = __builtin_bit_cast(float, b0 & 0xffff0000u) + a[1];
;                         const float o2 = __builtin_bit_cast(float, b1 << 16) + a[2], o3 = __builtin_bit_cast(float, b1 & 0xffff0000u) + a[3];
;                         sq += (o0 * o0 + o1 * o1) + (o2 * o2 + o3 * o3);
;                         w[2 * n] = cvt_pk_bf16(o0, o1); w[2 * n + 1] = cvt_pk_bf16(o2, o3); }
;                     *(u32x4*)(xp + bj * HALF) = w; }
;                 if (ss) { sq += __shfl_xor(sq, 16); sq += __shfl_xor(sq, 32); if (fq == 0) __hip_atomic_fetch_add(ss + row, (unsigned long long)(sq * 262144.f + 0.5f), __ATOMIC_RELAXED, __HIP_MEMORY_SCOPE_AGENT); } }
; template <class Epi, class Sched, bool ALIGN_EPI = false, bool SP2 = false>
; __device__ __forceinline__ void gemm_phase(PG8_LAS unsigned char* lds, const Gemm g, const Sched& S, const Epi& E) {
;     ...
;         if constexpr (ALIGN_EPI) { if (wr == 0) PG8_BAR; }
.LBB0_226:
	v_lshl_add_u32 v140, s62, 8, v144
	v_ashrrev_i32_e32 v141, 31, v140
	v_lshl_or_b32 v142, s63, 8, v146
	v_lshlrev_b64 v[148:149], 12, v[140:141]
	v_ashrrev_i32_e32 v143, 31, v142
	v_lshl_add_u64 v[148:149], s[18:19], 0, v[148:149]
	v_lshl_add_u64 v[160:161], v[142:143], 1, v[148:149]
	global_load_dwordx4 v[162:165], v[160:161], off
	global_load_dwordx4 v[166:169], v[160:161], off offset:256
	v_add_co_u32_e32 v154, vcc, 0x10000, v160
	s_nop 1
	v_addc_co_u32_e32 v155, vcc, 0, v161, vcc
	global_load_dwordx4 v[170:173], v[154:155], off
	global_load_dwordx4 v[174:177], v[154:155], off offset:256
	v_add_co_u32_e32 v154, vcc, 0x20000, v160
	s_nop 1
	v_addc_co_u32_e32 v155, vcc, 0, v161, vcc
	global_load_dwordx4 v[178:181], v[154:155], off
	global_load_dwordx4 v[182:185], v[154:155], off offset:256
	v_add_co_u32_e32 v154, vcc, 0x30000, v160
	s_nop 1
	v_addc_co_u32_e32 v155, vcc, 0, v161, vcc
	global_load_dwordx4 v[186:189], v[154:155], off
	global_load_dwordx4 v[190:193], v[154:155], off offset:256
	v_add_co_u32_e32 v154, vcc, 0x80000, v160
	s_nop 1
	v_addc_co_u32_e32 v155, vcc, 0, v161, vcc
	global_load_dwordx4 v[194:197], v[154:155], off
	global_load_dwordx4 v[198:201], v[154:155], off offset:256
	v_add_co_u32_e32 v202, vcc, 0x90000, v160
	s_nop 1
	v_addc_co_u32_e32 v203, vcc, 0, v161, vcc
	v_add_co_u32_e32 v204, vcc, 0xa0000, v160
	s_nop 1
	v_addc_co_u32_e32 v205, vcc, 0, v161, vcc
	v_add_co_u32_e32 v206, vcc, 0xb0000, v160
	s_nop 1
	v_addc_co_u32_e32 v207, vcc, 0, v161, vcc
	s_and_b64 vcc, exec, s[46:47]
	s_cbranch_vccz .Lalign_res
	s_barrier
.Lalign_res:
	s_andn2_b64 vcc, exec, s[48:49]
	s_waitcnt vmcnt(8)
	v_mov_b32_e32 v148, v162
	v_mov_b32_e32 v149, v163
	v_mov_b32_e32 v150, v164
	v_mov_b32_e32 v151, v165
	v_mov_b32_e32 v152, v166
	v_mov_b32_e32 v153, v167
	v_mov_b32_e32 v154, v168
	v_mov_b32_e32 v155, v169
	global_load_dwordx4 v[162:165], v[202:203], off
	global_load_dwordx4 v[166:169], v[202:203], off offset:256
	v_lshlrev_b32_e32 v156, 16, v148
	v_and_b32_e32 v148, 0xffff0000, v148
	v_add_f32_e32 v148, v127, v148
	v_lshlrev_b32_e32 v127, 16, v149
	v_add_f32_e32 v127, v128, v127
	v_and_b32_e32 v128, 0xffff0000, v149
	v_add_f32_e32 v128, v129, v128
	v_lshlrev_b32_e32 v129, 16, v150
	v_add_f32_e32 v122, v122, v129
	v_and_b32_e32 v129, 0xffff0000, v150
	v_add_f32_e32 v129, v123, v129
	v_lshlrev_b32_e32 v123, 16, v151
	v_add_f32_e32 v123, v124, v123
	v_and_b32_e32 v124, 0xffff0000, v151
	v_add_f32_e32 v124, v125, v124
	v_lshlrev_b32_e32 v125, 16, v152
	v_add_f32_e32 v118, v118, v125
	v_and_b32_e32 v125, 0xffff0000, v152
	v_add_f32_e32 v125, v119, v125
	v_lshlrev_b32_e32 v119, 16, v153
	v_add_f32_e32 v119, v120, v119
	v_and_b32_e32 v120, 0xffff0000, v153
	v_add_f32_e32 v120, v121, v120
	v_lshlrev_b32_e32 v121, 16, v154
	v_add_f32_e32 v114, v114, v121
	v_and_b32_e32 v121, 0xffff0000, v154
	v_add_f32_e32 v121, v115, v121
	v_lshlrev_b32_e32 v115, 16, v155
	v_add_f32_e32 v115, v116, v115
	v_and_b32_e32 v116, 0xffff0000, v155
	v_add_f32_e32 v116, v117, v116
	v_cndmask_b32_e64 v117, 0, 1, s[48:49]
	v_add_f32_e32 v126, v126, v156
	v_cmp_ne_u32_e64 s[44:45], 1, v117
	v_cvt_pk_bf16_f32 v156, v126, v148
	v_cvt_pk_bf16_f32 v157, v127, v128
	v_cvt_pk_bf16_f32 v158, v122, v129
	v_cvt_pk_bf16_f32 v159, v123, v124
	global_store_dwordx4 v[160:161], v[156:159], off
	v_cvt_pk_bf16_f32 v150, v118, v125
	v_cvt_pk_bf16_f32 v151, v119, v120
	v_cvt_pk_bf16_f32 v152, v114, v121
	v_cvt_pk_bf16_f32 v153, v115, v116
	global_store_dwordx4 v[160:161], v[150:153], off offset:256
	s_cbranch_vccnz .LBB0_230
	v_mul_f32_e32 v117, v148, v148
	v_fmac_f32_e32 v117, v126, v126
	v_mul_f32_e32 v126, v128, v128
	v_fmac_f32_e32 v126, v127, v127
	v_add_f32_e32 v117, v117, v126
	v_mul_f32_e32 v126, v129, v129
	v_fmac_f32_e32 v126, v122, v122
	v_mul_f32_e32 v122, v124, v124
	v_fmac_f32_e32 v122, v123, v123
	v_add_f32_e32 v122, v126, v122
	v_add_f32_e32 v117, v117, v122
	v_mul_f32_e32 v122, v125, v125
	v_fmac_f32_e32 v122, v118, v118
	v_mul_f32_e32 v118, v120, v120
	v_fmac_f32_e32 v118, v119, v119
	v_add_f32_e32 v118, v122, v118
	v_add_f32_e32 v117, v117, v118
	v_mul_f32_e32 v118, v121, v121
	v_fmac_f32_e32 v118, v114, v114
	v_mul_f32_e32 v114, v116, v116
	v_fmac_f32_e32 v114, v115, v115
	v_xor_b32_e32 v115, 16, v235
	v_add_u32_e32 v116, 64, v236
	v_cmp_lt_i32_e32 vcc, v115, v116
	v_add_f32_e32 v114, v118, v114
	v_add_f32_e32 v114, v114, v117
	v_cndmask_b32_e32 v115, v235, v115, vcc
	v_lshlrev_b32_e32 v115, 2, v115
	ds_bpermute_b32 v115, v115, v114
	s_waitcnt lgkmcnt(0)
	v_add_f32_e32 v114, v114, v115
	v_xor_b32_e32 v115, 32, v235
	v_cmp_lt_i32_e32 vcc, v115, v116
	s_nop 1
	v_cndmask_b32_e32 v115, v235, v115, vcc
	v_lshlrev_b32_e32 v115, 2, v115
	ds_bpermute_b32 v115, v115, v114
	s_and_saveexec_b64 s[8:9], s[40:41]
	s_cbranch_execz .LBB0_229
	s_waitcnt lgkmcnt(0)
	v_add_f32_e32 v114, v114, v115
	v_fma_f32 v114, v114, s88, 0.5
	v_trunc_f32_e32 v114, v114
	v_mul_f32_e32 v115, 0x2f800000, v114
	v_floor_f32_e32 v115, v115
	v_fmac_f32_e32 v114, 0xcf800000, v115
	v_cvt_u32_f32_e32 v114, v114
	v_cvt_u32_f32_e32 v115, v115
	v_lshl_add_u64 v[116:117], v[140:141], 3, s[36:37]
	global_atomic_add_x2 v[116:117], v[114:115], off

; #define PG8_STAGE(bufoff, gbase, voff) do { _Pragma("unroll") for (int _i = 0; _i < 2; ++_i) \
;         __builtin_amdgcn_global_load_lds((const unsigned*)((const char*)(gbase) + (voff)[_i]), (PG8_LAS unsigned*)(lds + (bufoff) + ldsw + _i * 8192), 16, 0, 0); } while (0)
; #define PG8_LDA(dst, b, h) do { _Pragma("unroll") for (int m = 0; m < 4; ++m) _Pragma("unroll") for (int k = 0; k < 2; ++k) dst[m][k] = *(const PG8_LAS bf16x8*)(lds + PG8_SA(b, h) + aoff + m * 2048 + k * 1024); } while (0)
; #define PG8_LDB(dst, b, h) do { _Pragma("unroll") for (int n = 0; n < 2; ++n) _Pragma("unroll") for (int k = 0; k < 2; ++k) dst[n][k] = *(const PG8_LAS bf16x8*)(lds + PG8_SB(b, h) + boff + n * 2048 + k * 1024); } while (0)
; #define PG8_MMA(ai, bj, At, Bt) do { __builtin_amdgcn_s_setprio(1); _Pragma("unroll") for (int m = 0; m < 4; ++m) _Pragma("unroll") for (int n = 0; n < 2; ++n) _Pragma("unroll") for (int k = 0; k < 2; ++k) \
;         acc[ai][bj][m][n] = __builtin_amdgcn_mfma_f32_16x16x32_bf16(Bt[n][k], At[m][k], acc[ai][bj][m][n], 0, 0, 0); __builtin_amdgcn_s_setprio(0); } while (0)
; #define PG8_WAIT_V(n) asm volatile("s_waitcnt vmcnt(" #n ")" ::: "memory")
; #define PG8_WAIT_L(n) asm volatile("s_waitcnt lgkmcnt(" #n ")" ::: "memory")
; #define PG8_BAR __builtin_amdgcn_s_barrier()
; #define PG8_SCHED __builtin_amdgcn_sched_barrier(0)
; template <class Epi, class Sched, bool ALIGN_EPI = false, bool SP2 = false>
; __device__ __forceinline__ void gemm_phase(PG8_LAS unsigned char* lds, const Gemm g, const Sched& S, const Epi& E) {
;     ...
;             PG8_LDB(B0, 0, 0); PG8_LDB(B1, 0, 1); PG8_SCHED; PG8_LDA(At, 0, 0); PG8_STAGE(PG8_SA(1, 1), a1 + hstep, voffA);
;             PG8_WAIT_V(8); PG8_WAIT_L(0); PG8_BAR; PG8_MMA(0, 0, At, B0); PG8_MMA(0, 1, At, B1); PG8_BAR; PG8_SCHED;
;             PG8_LDA(At, 0, 1); PG8_STAGE(PG8_SB(0, 0), b2, voffB); PG8_STAGE(PG8_SB(0, 1), b2 + hstep, voffB); PG8_STAGE(PG8_SA(0, 0), a2, voffA);
;             PG8_WAIT_V(8); PG8_WAIT_L(0); PG8_BAR; PG8_MMA(1, 0, At, B0); PG8_MMA(1, 1, At, B1); PG8_BAR; PG8_SCHED;
.LBB0_559:
	s_add_u32 s10, s50, 0xfff80080
	s_addc_u32 s11, s51, -1
	s_add_i32 s60, 0, 0x10000
	s_cmp_eq_u32 s59, 28
	s_cselect_b32 s53, s37, s11
	s_cselect_b32 s52, s43, s10
	s_cselect_b32 s11, s23, s58
	s_cselect_b32 s10, s56, s57
	s_add_i32 s62, 0, 0x14000
	ds_read_b128 v[140:143], v248
	ds_read_b128 v[152:155], v248 offset:1024
	ds_read_b128 v[156:159], v248 offset:2048
	ds_read_b128 v[160:163], v248 offset:3072
	ds_read_b128 v[164:167], v248 offset:16384
	ds_read_b128 v[168:171], v248 offset:17408
	ds_read_b128 v[172:175], v248 offset:18432
	ds_read_b128 v[176:179], v248 offset:19456
	s_add_i32 m0, s5, 0xc000
	ds_read_b128 v[180:183], v151
	ds_read_b128 v[184:187], v151 offset:1024
	ds_read_b128 v[188:191], v151 offset:2048
	ds_read_b128 v[192:195], v151 offset:3072
	ds_read_b128 v[196:199], v151 offset:4096
	ds_read_b128 v[200:203], v151 offset:5120
	ds_read_b128 v[204:207], v151 offset:6144
	ds_read_b128 v[208:211], v151 offset:7168
	global_load_lds_dwordx4 v136, s[50:51]
	s_add_i32 m0, s5, 0xe000
	s_nop 0
	global_load_lds_dwordx4 v138, s[50:51]
	s_waitcnt vmcnt(8) lgkmcnt(0)
	s_setprio 1
	s_barrier
	v_mfma_f32_16x16x32_bf16 v[126:129], v[140:143], v[180:183], v[126:129]
	v_mfma_f32_16x16x32_bf16 v[122:125], v[156:159], v[180:183], v[122:125]
	v_mfma_f32_16x16x32_bf16 v[110:113], v[140:143], v[188:191], v[110:113]
	v_mfma_f32_16x16x32_bf16 v[106:109], v[156:159], v[188:191], v[106:109]
	v_mfma_f32_16x16x32_bf16 v[94:97], v[140:143], v[196:199], v[94:97]
	v_mfma_f32_16x16x32_bf16 v[90:93], v[156:159], v[196:199], v[90:93]
	v_mfma_f32_16x16x32_bf16 v[78:81], v[140:143], v[204:207], v[78:81]
	v_mfma_f32_16x16x32_bf16 v[74:77], v[156:159], v[204:207], v[74:77]
	v_mfma_f32_16x16x32_bf16 v[126:129], v[152:155], v[184:187], v[126:129]
	v_mfma_f32_16x16x32_bf16 v[122:125], v[160:163], v[184:187], v[122:125]
	v_mfma_f32_16x16x32_bf16 v[110:113], v[152:155], v[192:195], v[110:113]
	v_mfma_f32_16x16x32_bf16 v[106:109], v[160:163], v[192:195], v[106:109]
	v_mfma_f32_16x16x32_bf16 v[94:97], v[152:155], v[200:203], v[94:97]
	v_mfma_f32_16x16x32_bf16 v[90:93], v[160:163], v[200:203], v[90:93]
	v_mfma_f32_16x16x32_bf16 v[78:81], v[152:155], v[208:211], v[78:81]
	v_mfma_f32_16x16x32_bf16 v[74:77], v[160:163], v[208:211], v[74:77]
	v_mfma_f32_16x16x32_bf16 v[118:121], v[164:167], v[180:183], v[118:121]
	v_mfma_f32_16x16x32_bf16 v[114:117], v[172:175], v[180:183], v[114:117]
	v_mfma_f32_16x16x32_bf16 v[102:105], v[164:167], v[188:191], v[102:105]
	v_mfma_f32_16x16x32_bf16 v[98:101], v[172:175], v[188:191], v[98:101]
	v_mfma_f32_16x16x32_bf16 v[86:89], v[164:167], v[196:199], v[86:89]
	v_mfma_f32_16x16x32_bf16 v[82:85], v[172:175], v[196:199], v[82:85]
	v_mfma_f32_16x16x32_bf16 v[70:73], v[164:167], v[204:207], v[70:73]
	v_mfma_f32_16x16x32_bf16 v[66:69], v[172:175], v[204:207], v[66:69]
	v_mfma_f32_16x16x32_bf16 v[118:121], v[168:171], v[184:187], v[118:121]
	v_mfma_f32_16x16x32_bf16 v[114:117], v[176:179], v[184:187], v[114:117]
	v_mfma_f32_16x16x32_bf16 v[102:105], v[168:171], v[192:195], v[102:105]
	v_mfma_f32_16x16x32_bf16 v[98:101], v[176:179], v[192:195], v[98:101]
	v_mfma_f32_16x16x32_bf16 v[86:89], v[168:171], v[200:203], v[86:89]
	v_mfma_f32_16x16x32_bf16 v[82:85], v[176:179], v[200:203], v[82:85]
	v_mfma_f32_16x16x32_bf16 v[70:73], v[168:171], v[208:211], v[70:73]
	v_mfma_f32_16x16x32_bf16 v[66:69], v[176:179], v[208:211], v[66:69]
	s_barrier
	s_setprio 0
	s_add_i32 s60, s60, s4
	s_add_u32 s100, s10, 0x80
	s_addc_u32 s101, s11, 0
	s_mov_b32 m0, s60
	ds_read_b128 v[180:183], v151 offset:16384
	ds_read_b128 v[184:187], v151 offset:17408
	ds_read_b128 v[188:191], v151 offset:18432
	ds_read_b128 v[192:195], v151 offset:19456
	ds_read_b128 v[196:199], v151 offset:20480
	ds_read_b128 v[200:203], v151 offset:21504
	ds_read_b128 v[204:207], v151 offset:22528
	ds_read_b128 v[208:211], v151 offset:23552
	global_load_lds_dwordx4 v0, s[10:11]
	s_add_i32 m0, s60, 0x2000
	s_add_u32 s60, s10, 0x80000
	s_addc_u32 s61, s11, 0
	s_add_i32 s62, s62, s4
	global_load_lds_dwordx4 v134, s[10:11]
	s_mov_b32 m0, s62
	s_add_u32 s98, s52, 0x80
	s_addc_u32 s99, s53, 0
	global_load_lds_dwordx4 v0, s[60:61]
	s_add_i32 m0, s62, 0x2000
	s_nop 0
	global_load_lds_dwordx4 v134, s[60:61]
	s_mov_b32 m0, s5
	s_nop 0
	global_load_lds_dwordx4 v130, s[52:53]
	s_mov_b32 m0, s6
	s_nop 0
	global_load_lds_dwordx4 v132, s[52:53]
	s_waitcnt vmcnt(8) lgkmcnt(0)
	s_setprio 1
	s_barrier
	v_mfma_f32_16x16x32_bf16 v[62:65], v[140:143], v[180:183], v[62:65]
	v_mfma_f32_16x16x32_bf16 v[58:61], v[156:159], v[180:183], v[58:61]
	v_mfma_f32_16x16x32_bf16 v[46:49], v[140:143], v[188:191], v[46:49]
	v_mfma_f32_16x16x32_bf16 v[42:45], v[156:159], v[188:191], v[42:45]
	v_mfma_f32_16x16x32_bf16 v[30:33], v[140:143], v[196:199], v[30:33]
	v_mfma_f32_16x16x32_bf16 v[26:29], v[156:159], v[196:199], v[26:29]
	v_mfma_f32_16x16x32_bf16 v[14:17], v[140:143], v[204:207], v[14:17]
	v_mfma_f32_16x16x32_bf16 v[10:13], v[156:159], v[204:207], v[10:13]
	v_mfma_f32_16x16x32_bf16 v[62:65], v[152:155], v[184:187], v[62:65]
	v_mfma_f32_16x16x32_bf16 v[58:61], v[160:163], v[184:187], v[58:61]
	v_mfma_f32_16x16x32_bf16 v[46:49], v[152:155], v[192:195], v[46:49]
	v_mfma_f32_16x16x32_bf16 v[42:45], v[160:163], v[192:195], v[42:45]
	v_mfma_f32_16x16x32_bf16 v[30:33], v[152:155], v[200:203], v[30:33]
	v_mfma_f32_16x16x32_bf16 v[26:29], v[160:163], v[200:203], v[26:29]
	v_mfma_f32_16x16x32_bf16 v[14:17], v[152:155], v[208:211], v[14:17]
	v_mfma_f32_16x16x32_bf16 v[10:13], v[160:163], v[208:211], v[10:13]
	v_mfma_f32_16x16x32_bf16 v[54:57], v[164:167], v[180:183], v[54:57]
	v_mfma_f32_16x16x32_bf16 v[50:53], v[172:175], v[180:183], v[50:53]
	v_mfma_f32_16x16x32_bf16 v[38:41], v[164:167], v[188:191], v[38:41]
	v_mfma_f32_16x16x32_bf16 v[34:37], v[172:175], v[188:191], v[34:37]
	v_mfma_f32_16x16x32_bf16 v[22:25], v[164:167], v[196:199], v[22:25]
	v_mfma_f32_16x16x32_bf16 v[18:21], v[172:175], v[196:199], v[18:21]
	v_mfma_f32_16x16x32_bf16 v[6:9], v[164:167], v[204:207], v[6:9]
	v_mfma_f32_16x16x32_bf16 v[2:5], v[172:175], v[204:207], v[2:5]
	v_mfma_f32_16x16x32_bf16 v[54:57], v[168:171], v[184:187], v[54:57]
	v_mfma_f32_16x16x32_bf16 v[50:53], v[176:179], v[184:187], v[50:53]
	v_mfma_f32_16x16x32_bf16 v[38:41], v[168:171], v[192:195], v[38:41]
	v_mfma_f32_16x16x32_bf16 v[34:37], v[176:179], v[192:195], v[34:37]
	v_mfma_f32_16x16x32_bf16 v[22:25], v[168:171], v[200:203], v[22:25]
	v_mfma_f32_16x16x32_bf16 v[18:21], v[176:179], v[200:203], v[18:21]
	v_mfma_f32_16x16x32_bf16 v[6:9], v[168:171], v[208:211], v[6:9]
	v_mfma_f32_16x16x32_bf16 v[2:5], v[176:179], v[208:211], v[2:5]
	s_barrier
; #define PG8_STAGE(bufoff, gbase, voff) do { _Pragma("unroll") for (int _i = 0; _i < 2; ++_i) \
;         __builtin_amdgcn_global_load_lds((const unsigned*)((const char*)(gbase) + (voff)[_i]), (PG8_LAS unsigned*)(lds + (bufoff) + ldsw + _i * 8192), 16, 0, 0); } while (0)
; #define PG8_LDA(dst, b, h) do { _Pragma("unroll") for (int m = 0; m < 4; ++m) _Pragma("unroll") for (int k = 0; k < 2; ++k) dst[m][k] = *(const PG8_LAS bf16x8*)(lds + PG8_SA(b, h) + aoff + m * 2048 + k * 1024); } while (0)
; #define PG8_LDB(dst, b, h) do { _Pragma("unroll") for (int n = 0; n < 2; ++n) _Pragma("unroll") for (int k = 0; k < 2; ++k) dst[n][k] = *(const PG8_LAS bf16x8*)(lds + PG8_SB(b, h) + boff + n * 2048 + k * 1024); } while (0)
; #define PG8_MMA(ai, bj, At, Bt) do { __builtin_amdgcn_s_setprio(1); _Pragma("unroll") for (int m = 0; m < 4; ++m) _Pragma("unroll") for (int n = 0; n < 2; ++n) _Pragma("unroll") for (int k = 0; k < 2; ++k) \
;         acc[ai][bj][m][n] = __builtin_amdgcn_mfma_f32_16x16x32_bf16(Bt[n][k], At[m][k], acc[ai][bj][m][n], 0, 0, 0); __builtin_amdgcn_s_setprio(0); } while (0)
; #define PG8_WAIT_V(n) asm volatile("s_waitcnt vmcnt(" #n ")" ::: "memory")
; #define PG8_WAIT_L(n) asm volatile("s_waitcnt lgkmcnt(" #n ")" ::: "memory")
; #define PG8_BAR __builtin_amdgcn_s_barrier()
; #define PG8_SCHED __builtin_amdgcn_sched_barrier(0)
; template <class Epi, class Sched, bool ALIGN_EPI = false, bool SP2 = false>
; __device__ __forceinline__ void gemm_phase(PG8_LAS unsigned char* lds, const Gemm g, const Sched& S, const Epi& E) {
;     ...
;             PG8_LDB(B0, 1, 0); PG8_LDB(B1, 1, 1); PG8_SCHED; PG8_LDA(At, 1, 0); PG8_STAGE(PG8_SA(0, 1), a2 + hstep, voffA);
;             PG8_WAIT_V(8); PG8_WAIT_L(0); PG8_BAR; PG8_MMA(0, 0, At, B0); PG8_MMA(0, 1, At, B1); PG8_BAR; PG8_SCHED;
;             PG8_LDA(At, 1, 1); PG8_STAGE(PG8_SB(1, 0), b3, voffB); PG8_STAGE(PG8_SB(1, 1), b3 + hstep, voffB); PG8_STAGE(PG8_SA(1, 0), a3, voffA);
;             PG8_WAIT_V(8); PG8_WAIT_L(0); PG8_BAR; PG8_MMA(1, 0, At, B0); PG8_MMA(1, 1, At, B1); PG8_BAR; PG8_SCHED;
	s_setprio 0
	s_add_i32 s60, 0, 0x18000
	s_add_i32 s61, 0, 0x1c000
	ds_read_b128 v[140:143], v248 offset:32768
	ds_read_b128 v[152:155], v248 offset:33792
	ds_read_b128 v[156:159], v248 offset:34816
	ds_read_b128 v[160:163], v248 offset:35840
	ds_read_b128 v[164:167], v248 offset:49152
	ds_read_b128 v[168:171], v248 offset:50176
	ds_read_b128 v[172:175], v248 offset:51200
	ds_read_b128 v[176:179], v248 offset:52224
	s_add_u32 s52, s52, 0x80000
	s_addc_u32 s53, s53, 0
	s_mov_b32 m0, s7
	ds_read_b128 v[180:183], v151 offset:32768
	ds_read_b128 v[184:187], v151 offset:33792
	ds_read_b128 v[188:191], v151 offset:34816
	ds_read_b128 v[192:195], v151 offset:35840
	ds_read_b128 v[196:199], v151 offset:36864
	ds_read_b128 v[200:203], v151 offset:37888
	ds_read_b128 v[204:207], v151 offset:38912
	ds_read_b128 v[208:211], v151 offset:39936
	global_load_lds_dwordx4 v130, s[52:53]
	s_mov_b32 m0, s17
	s_nop 0
	global_load_lds_dwordx4 v132, s[52:53]
	s_waitcnt vmcnt(8) lgkmcnt(0)
	s_setprio 1
	s_barrier
	v_mfma_f32_16x16x32_bf16 v[126:129], v[140:143], v[180:183], v[126:129]
	v_mfma_f32_16x16x32_bf16 v[122:125], v[156:159], v[180:183], v[122:125]
	v_mfma_f32_16x16x32_bf16 v[110:113], v[140:143], v[188:191], v[110:113]
	v_mfma_f32_16x16x32_bf16 v[106:109], v[156:159], v[188:191], v[106:109]
	v_mfma_f32_16x16x32_bf16 v[94:97], v[140:143], v[196:199], v[94:97]
	v_mfma_f32_16x16x32_bf16 v[90:93], v[156:159], v[196:199], v[90:93]
	v_mfma_f32_16x16x32_bf16 v[78:81], v[140:143], v[204:207], v[78:81]
	v_mfma_f32_16x16x32_bf16 v[74:77], v[156:159], v[204:207], v[74:77]
	v_mfma_f32_16x16x32_bf16 v[126:129], v[152:155], v[184:187], v[126:129]
	v_mfma_f32_16x16x32_bf16 v[122:125], v[160:163], v[184:187], v[122:125]
	v_mfma_f32_16x16x32_bf16 v[110:113], v[152:155], v[192:195], v[110:113]
	v_mfma_f32_16x16x32_bf16 v[106:109], v[160:163], v[192:195], v[106:109]
	v_mfma_f32_16x16x32_bf16 v[94:97], v[152:155], v[200:203], v[94:97]
	v_mfma_f32_16x16x32_bf16 v[90:93], v[160:163], v[200:203], v[90:93]
	v_mfma_f32_16x16x32_bf16 v[78:81], v[152:155], v[208:211], v[78:81]
	v_mfma_f32_16x16x32_bf16 v[74:77], v[160:163], v[208:211], v[74:77]
	v_mfma_f32_16x16x32_bf16 v[118:121], v[164:167], v[180:183], v[118:121]
	v_mfma_f32_16x16x32_bf16 v[114:117], v[172:175], v[180:183], v[114:117]
	v_mfma_f32_16x16x32_bf16 v[102:105], v[164:167], v[188:191], v[102:105]
	v_mfma_f32_16x16x32_bf16 v[98:101], v[172:175], v[188:191], v[98:101]
	v_mfma_f32_16x16x32_bf16 v[86:89], v[164:167], v[196:199], v[86:89]
	v_mfma_f32_16x16x32_bf16 v[82:85], v[172:175], v[196:199], v[82:85]
	v_mfma_f32_16x16x32_bf16 v[70:73], v[164:167], v[204:207], v[70:73]
	v_mfma_f32_16x16x32_bf16 v[66:69], v[172:175], v[204:207], v[66:69]
	v_mfma_f32_16x16x32_bf16 v[118:121], v[168:171], v[184:187], v[118:121]
	v_mfma_f32_16x16x32_bf16 v[114:117], v[176:179], v[184:187], v[114:117]
	v_mfma_f32_16x16x32_bf16 v[102:105], v[168:171], v[192:195], v[102:105]
	v_mfma_f32_16x16x32_bf16 v[98:101], v[176:179], v[192:195], v[98:101]
	v_mfma_f32_16x16x32_bf16 v[86:89], v[168:171], v[200:203], v[86:89]
	v_mfma_f32_16x16x32_bf16 v[82:85], v[176:179], v[200:203], v[82:85]
	v_mfma_f32_16x16x32_bf16 v[70:73], v[168:171], v[208:211], v[70:73]
	v_mfma_f32_16x16x32_bf16 v[66:69], v[176:179], v[208:211], v[66:69]
	s_barrier
	s_setprio 0
	s_add_i32 s52, s60, s4
	s_mov_b32 m0, s52
	ds_read_b128 v[180:183], v151 offset:49152
	ds_read_b128 v[184:187], v151 offset:50176
	ds_read_b128 v[188:191], v151 offset:51200
	ds_read_b128 v[192:195], v151 offset:52224
	ds_read_b128 v[196:199], v151 offset:53248
	ds_read_b128 v[200:203], v151 offset:54272
	ds_read_b128 v[204:207], v151 offset:55296
	ds_read_b128 v[208:211], v151 offset:56320
	global_load_lds_dwordx4 v0, s[100:101]
	s_add_i32 m0, s52, 0x2000
	s_add_i32 s52, s61, s4
	global_load_lds_dwordx4 v134, s[100:101]
	s_add_u32 s10, s10, 0x80080
	s_addc_u32 s11, s11, 0
	s_mov_b32 m0, s52
	s_nop 0
	global_load_lds_dwordx4 v0, s[10:11]
	s_add_i32 m0, s52, 0x2000
	s_nop 0
	global_load_lds_dwordx4 v134, s[10:11]
	s_mov_b32 m0, s30
	s_nop 0
	global_load_lds_dwordx4 v130, s[98:99]
	s_mov_b32 m0, s47
	s_nop 0
	global_load_lds_dwordx4 v132, s[98:99]
	s_waitcnt vmcnt(8) lgkmcnt(0)
	s_setprio 1
	s_barrier
	v_mfma_f32_16x16x32_bf16 v[62:65], v[140:143], v[180:183], v[62:65]
	v_mfma_f32_16x16x32_bf16 v[58:61], v[156:159], v[180:183], v[58:61]
	v_mfma_f32_16x16x32_bf16 v[46:49], v[140:143], v[188:191], v[46:49]
	v_mfma_f32_16x16x32_bf16 v[42:45], v[156:159], v[188:191], v[42:45]
	v_mfma_f32_16x16x32_bf16 v[30:33], v[140:143], v[196:199], v[30:33]
	v_mfma_f32_16x16x32_bf16 v[26:29], v[156:159], v[196:199], v[26:29]
	v_mfma_f32_16x16x32_bf16 v[14:17], v[140:143], v[204:207], v[14:17]
	v_mfma_f32_16x16x32_bf16 v[10:13], v[156:159], v[204:207], v[10:13]
	v_mfma_f32_16x16x32_bf16 v[62:65], v[152:155], v[184:187], v[62:65]
	v_mfma_f32_16x16x32_bf16 v[58:61], v[160:163], v[184:187], v[58:61]
	v_mfma_f32_16x16x32_bf16 v[46:49], v[152:155], v[192:195], v[46:49]
	v_mfma_f32_16x16x32_bf16 v[42:45], v[160:163], v[192:195], v[42:45]
	v_mfma_f32_16x16x32_bf16 v[30:33], v[152:155], v[200:203], v[30:33]
	v_mfma_f32_16x16x32_bf16 v[26:29], v[160:163], v[200:203], v[26:29]
	v_mfma_f32_16x16x32_bf16 v[14:17], v[152:155], v[208:211], v[14:17]
	v_mfma_f32_16x16x32_bf16 v[10:13], v[160:163], v[208:211], v[10:13]
	v_mfma_f32_16x16x32_bf16 v[54:57], v[164:167], v[180:183], v[54:57]
	v_mfma_f32_16x16x32_bf16 v[50:53], v[172:175], v[180:183], v[50:53]
	v_mfma_f32_16x16x32_bf16 v[38:41], v[164:167], v[188:191], v[38:41]
	v_mfma_f32_16x16x32_bf16 v[34:37], v[172:175], v[188:191], v[34:37]
	v_mfma_f32_16x16x32_bf16 v[22:25], v[164:167], v[196:199], v[22:25]
	v_mfma_f32_16x16x32_bf16 v[18:21], v[172:175], v[196:199], v[18:21]
	v_mfma_f32_16x16x32_bf16 v[6:9], v[164:167], v[204:207], v[6:9]
	v_mfma_f32_16x16x32_bf16 v[2:5], v[172:175], v[204:207], v[2:5]
	v_mfma_f32_16x16x32_bf16 v[54:57], v[168:171], v[184:187], v[54:57]
	v_mfma_f32_16x16x32_bf16 v[50:53], v[176:179], v[184:187], v[50:53]
	v_mfma_f32_16x16x32_bf16 v[38:41], v[168:171], v[192:195], v[38:41]
	v_mfma_f32_16x16x32_bf16 v[34:37], v[176:179], v[192:195], v[34:37]
	v_mfma_f32_16x16x32_bf16 v[22:25], v[168:171], v[200:203], v[22:25]
	v_mfma_f32_16x16x32_bf16 v[18:21], v[176:179], v[200:203], v[18:21]
	v_mfma_f32_16x16x32_bf16 v[6:9], v[168:171], v[208:211], v[6:9]
	v_mfma_f32_16x16x32_bf16 v[2:5], v[176:179], v[208:211], v[2:5]
	s_barrier
	s_setprio 0
	s_add_i32 s59, s59, 2
	s_add_u32 s50, s50, 0x100
	s_addc_u32 s51, s51, 0
	s_add_u32 s57, s57, 0x100
	s_addc_u32 s58, s58, 0
	s_cmp_gt_u32 s59, 29
	s_cbranch_scc0 .LBB0_559
	s_and_b64 vcc, exec, s[14:15]
	s_cbranch_vccz .LBB0_562
; #define PG8_BAR __builtin_amdgcn_s_barrier()
;     __device__ __forceinline__ void operator()(const f32x4 (&acc)[2][2][4][2], const Unit& u, int wr, int wc, int fr, int fq) const {
;         const int row0 = u.pm * BM + wr * 64 + fr; const bool second = split > 0 && u.pn >= split; const int col0 = (second ? u.pn - split : u.pn) * BM + wc * 32 + 8 * fq;
;         bf16_t* const Ob = second ? O2 : O; const int ld = second ? ldc2 : ldc;
; #pragma unroll
;         for (int ai = 0; ai < 2; ++ai)
; #pragma unroll
;             for (int m = 0; m < 4; ++m) { bf16_t* rowp = Ob + (size_t)(row0 + ai * HALF + m * 16) * ld + col0;
;                 float rs = 1.f; if (ss) rs = __builtin_amdgcn_rsqf((float)ss[row0 + ai * HALF + m * 16] * (1.f / (2048.f * 262144.f)) + 1e-6f);
; template <class Epi, class Sched, bool ALIGN_EPI = false, bool SP2 = false>
; __device__ __forceinline__ void gemm_phase(PG8_LAS unsigned char* lds, const Gemm g, const Sched& S, const Epi& E) {
;     ...
;         if constexpr (ALIGN_EPI) { if (wr == 0) PG8_BAR; }
.LBB0_562:
	v_lshl_add_u32 v140, s42, 8, v147
	v_ashrrev_i32_e32 v141, 31, v140
	v_cndmask_b32_e64 v142, 0, 1, s[20:21]
	v_mov_b32_e32 v146, 1.0
	v_cmp_ne_u32_e64 s[42:43], 1, v142
	s_andn2_b64 vcc, exec, s[20:21]
	s_and_b32 s98, s55, 1
	s_lshl_b32 s98, s98, 12
	s_add_i32 s98, s98, 0x20000
	v_lshl_add_u32 v142, v147, 3, s98
	v_mov_b32_e32 v148, 1.0
	s_cbranch_vccnz .LBB0_564
	ds_read_b64 v[160:161], v142
	ds_read_b64 v[162:163], v142 offset:128
	ds_read_b64 v[164:165], v142 offset:256
	ds_read_b64 v[166:167], v142 offset:384
	ds_read_b64 v[168:169], v142 offset:1024
	ds_read_b64 v[170:171], v142 offset:1152
	ds_read_b64 v[172:173], v142 offset:1280
	ds_read_b64 v[174:175], v142 offset:1408
	s_waitcnt lgkmcnt(0)
	v_mov_b32_e32 v144, v160
	v_mov_b32_e32 v145, v161
	v_ffbh_u32_e32 v141, v145
	v_min_u32_e32 v141, 32, v141
	v_lshlrev_b64 v[144:145], v141, v[144:145]
	v_min_u32_e32 v144, 1, v144
	v_or_b32_e32 v144, v145, v144
	v_cvt_f32_u32_e32 v144, v144
	v_sub_u32_e32 v141, 32, v141
	v_ldexp_f32 v141, v144, v141
	v_fmamk_f32 v141, v141, 0x31000000, v232
	v_rsq_f32_e32 v148, v141
.LBB0_564:
	s_and_b64 vcc, exec, s[14:15]
	s_cbranch_vccz .Lalign_proj
	s_barrier
